# P5 EpiPle epilogue rewritten: three 8-column pieces of pp/x kept in flight with counted vmcnt waits instead of one load round trip per piece (same arithmetic); plus the attention packed->scalar split
# baseline (speedup 1.0000x reference)
.LBB0_975:
	v_lshl_add_u32 v172, s77, 8, v212
	s_lshl_b32 s11, s76, 2
	s_or_b32 s46, s11, s63
	s_ashr_i32 s47, s46, 31
	s_lshl_b64 s[46:47], s[46:47], 17
	s_add_u32 s76, s28, s46
	s_addc_u32 s77, s29, s47
	v_lshl_add_u32 v176, v172, 10, v182
	v_lshlrev_b32_e32 v177, 2, v172
	v_lshlrev_b32_e32 v176, 2, v176
	v_mov_b32_e32 v172, v176
	v_lshrrev_b32_e32 v190, 1, v172
	global_load_dwordx4 v[218:221], v190, s[36:37]
	global_load_dwordx4 v[222:225], v172, s[16:17]
	global_load_dwordx4 v[226:229], v172, s[16:17] offset:16
	v_mov_b32_e32 v173, v176
	v_lshrrev_b32_e32 v191, 1, v173
	global_load_dwordx4 v[230:233], v191, s[36:37] offset:256
	global_load_dwordx4 v[234:237], v173, s[16:17] offset:512
	global_load_dwordx4 v[238:241], v173, s[16:17] offset:528
	v_add_u32_e32 v217, 0x10000, v176
	v_lshrrev_b32_e32 v192, 1, v217
	global_load_dwordx4 v[242:245], v192, s[36:37]
	global_load_dwordx4 v[246:249], v217, s[16:17]
	global_load_dwordx4 v[186:189], v217, s[16:17] offset:16
	s_waitcnt lgkmcnt(0)
	v_mul_f32_e32 v138, v138, v184
	v_mul_f32_e32 v139, v139, v184
	v_mul_f32_e32 v140, v140, v184
	v_mul_f32_e32 v141, v141, v184
	v_mul_f32_e32 v142, v142, v184
	v_mul_f32_e32 v143, v143, v184
	v_mul_f32_e32 v144, v144, v184
	v_mul_f32_e32 v145, v145, v184
	v_mul_f32_e32 v138, 0xbfb8aa3b, v138
	v_mul_f32_e32 v139, 0xbfb8aa3b, v139
	v_mul_f32_e32 v140, 0xbfb8aa3b, v140
	v_mul_f32_e32 v141, 0xbfb8aa3b, v141
	v_mul_f32_e32 v142, 0xbfb8aa3b, v142
	v_mul_f32_e32 v143, 0xbfb8aa3b, v143
	v_mul_f32_e32 v144, 0xbfb8aa3b, v144
	v_mul_f32_e32 v145, 0xbfb8aa3b, v145
	v_exp_f32_e32 v138, v138
	v_exp_f32_e32 v139, v139
	v_exp_f32_e32 v140, v140
	v_exp_f32_e32 v141, v141
	v_exp_f32_e32 v142, v142
	v_exp_f32_e32 v143, v143
	v_exp_f32_e32 v144, v144
	v_exp_f32_e32 v145, v145
	v_add_f32_e32 v138, 1.0, v138
	v_add_f32_e32 v139, 1.0, v139
	v_add_f32_e32 v140, 1.0, v140
	v_add_f32_e32 v141, 1.0, v141
	v_add_f32_e32 v142, 1.0, v142
	v_add_f32_e32 v143, 1.0, v143
	v_add_f32_e32 v144, 1.0, v144
	v_add_f32_e32 v145, 1.0, v145
	v_rcp_f32_e32 v138, v138
	v_rcp_f32_e32 v139, v139
	v_rcp_f32_e32 v140, v140
	v_rcp_f32_e32 v141, v141
	v_rcp_f32_e32 v142, v142
	v_rcp_f32_e32 v143, v143
	v_rcp_f32_e32 v144, v144
	v_rcp_f32_e32 v145, v145
	s_waitcnt vmcnt(6)
	v_lshlrev_b32_e32 v190, 16, v218
	v_and_b32_e32 v191, 0xffff0000, v218
	v_lshlrev_b32_e32 v192, 16, v219
	v_and_b32_e32 v193, 0xffff0000, v219
	v_lshlrev_b32_e32 v194, 16, v220
	v_and_b32_e32 v195, 0xffff0000, v220
	v_lshlrev_b32_e32 v148, 16, v221
	v_and_b32_e32 v149, 0xffff0000, v221
	v_pk_fma_f32 v[222:223], v[142:143], v[190:191], v[222:223]
	v_pk_fma_f32 v[224:225], v[144:145], v[192:193], v[224:225]
	v_pk_fma_f32 v[226:227], v[138:139], v[194:195], v[226:227]
	v_pk_fma_f32 v[228:229], v[140:141], v[148:149], v[228:229]
	global_store_dwordx4 v172, v[222:225], s[16:17]
	global_store_dwordx4 v172, v[226:229], s[16:17] offset:16
	s_and_b64 vcc, exec, s[2:3]
	s_cbranch_vccnz .Lple_skip_0
	v_mul_f32_e32 v138, v223, v223
	v_mul_f32_e32 v139, v225, v225
	v_fmac_f32_e32 v138, v222, v222
	v_fmac_f32_e32 v139, v224, v224
	v_add_f32_e32 v138, v138, v139
	v_mul_f32_e32 v139, v227, v227
	v_fmac_f32_e32 v139, v226, v226
	v_add_f32_e32 v138, v139, v138
	v_mul_f32_e32 v139, v229, v229
	v_fmac_f32_e32 v139, v228, v228
	v_add_f32_e32 v138, v139, v138
	v_pk_mul_f32 v[190:191], v[62:63], v[222:223]
	v_pk_mul_f32 v[192:193], v[64:65], v[224:225]
	v_pk_mul_f32 v[194:195], v[58:59], v[226:227]
	v_pk_mul_f32 v[148:149], v[60:61], v[228:229]
	v_cvt_pk_bf16_f32 v142, v190, v191
	v_cvt_pk_bf16_f32 v143, v192, v193
	v_cvt_pk_bf16_f32 v144, v194, v195
	v_cvt_pk_bf16_f32 v145, v148, v149
	v_lshrrev_b32_e32 v140, 1, v172
	global_store_dwordx4 v140, v[142:145], s[30:31]
.Lple_skip_0:
	v_add_u32_e32 v172, 0x10000, v176
	v_lshrrev_b32_e32 v141, 1, v172
	global_load_dwordx4 v[218:221], v141, s[36:37] offset:256
	global_load_dwordx4 v[222:225], v172, s[16:17] offset:512
	global_load_dwordx4 v[226:229], v172, s[16:17] offset:528
	v_mul_f32_e32 v130, v130, v184
	v_mul_f32_e32 v131, v131, v184
	v_mul_f32_e32 v132, v132, v184
	v_mul_f32_e32 v133, v133, v184
	v_mul_f32_e32 v134, v134, v184
	v_mul_f32_e32 v135, v135, v184
	v_mul_f32_e32 v136, v136, v184
	v_mul_f32_e32 v137, v137, v184
	v_mul_f32_e32 v130, 0xbfb8aa3b, v130
	v_mul_f32_e32 v131, 0xbfb8aa3b, v131
	v_mul_f32_e32 v132, 0xbfb8aa3b, v132
	v_mul_f32_e32 v133, 0xbfb8aa3b, v133
	v_mul_f32_e32 v134, 0xbfb8aa3b, v134
	v_mul_f32_e32 v135, 0xbfb8aa3b, v135
	v_mul_f32_e32 v136, 0xbfb8aa3b, v136
	v_mul_f32_e32 v137, 0xbfb8aa3b, v137
	v_exp_f32_e32 v130, v130
	v_exp_f32_e32 v131, v131
	v_exp_f32_e32 v132, v132
	v_exp_f32_e32 v133, v133
	v_exp_f32_e32 v134, v134
	v_exp_f32_e32 v135, v135
	v_exp_f32_e32 v136, v136
	v_exp_f32_e32 v137, v137
	v_add_f32_e32 v130, 1.0, v130
	v_add_f32_e32 v131, 1.0, v131
	v_add_f32_e32 v132, 1.0, v132
	v_add_f32_e32 v133, 1.0, v133
	v_add_f32_e32 v134, 1.0, v134
	v_add_f32_e32 v135, 1.0, v135
	v_add_f32_e32 v136, 1.0, v136
	v_add_f32_e32 v137, 1.0, v137
	v_rcp_f32_e32 v130, v130
	v_rcp_f32_e32 v131, v131
	v_rcp_f32_e32 v132, v132
	v_rcp_f32_e32 v133, v133
	v_rcp_f32_e32 v134, v134
	v_rcp_f32_e32 v135, v135
	v_rcp_f32_e32 v136, v136
	v_rcp_f32_e32 v137, v137
	s_waitcnt vmcnt(8)
	v_lshlrev_b32_e32 v190, 16, v230
	v_and_b32_e32 v191, 0xffff0000, v230
	v_lshlrev_b32_e32 v192, 16, v231
	v_and_b32_e32 v193, 0xffff0000, v231
	v_lshlrev_b32_e32 v194, 16, v232
	v_and_b32_e32 v195, 0xffff0000, v232
	v_lshlrev_b32_e32 v148, 16, v233
	v_and_b32_e32 v149, 0xffff0000, v233
	v_pk_fma_f32 v[234:235], v[134:135], v[190:191], v[234:235]
	v_pk_fma_f32 v[236:237], v[136:137], v[192:193], v[236:237]
	v_pk_fma_f32 v[238:239], v[130:131], v[194:195], v[238:239]
	v_pk_fma_f32 v[240:241], v[132:133], v[148:149], v[240:241]
	global_store_dwordx4 v173, v[234:237], s[16:17] offset:512
	global_store_dwordx4 v173, v[238:241], s[16:17] offset:528
	s_and_b64 vcc, exec, s[2:3]
	s_cbranch_vccnz .Lple_skip_1
	v_mul_f32_e32 v130, v234, v234
	v_mul_f32_e32 v131, v235, v235
	v_mul_f32_e32 v132, v236, v236
	v_mul_f32_e32 v133, v237, v237
	v_add_f32_e32 v130, v130, v131
	v_add_f32_e32 v132, v132, v133
	v_mul_f32_e32 v131, v238, v238
	v_mul_f32_e32 v133, v239, v239
	v_add_f32_e32 v130, v130, v132
	v_add_f32_e32 v131, v131, v133
	v_mul_f32_e32 v132, v240, v240
	v_mul_f32_e32 v133, v241, v241
	v_add_f32_e32 v130, v131, v130
	v_add_f32_e32 v132, v132, v133
	v_add_f32_e32 v130, v132, v130
	v_add_f32_e32 v130, v138, v130
	v_pk_mul_f32 v[190:191], v[54:55], v[234:235]
	v_pk_mul_f32 v[192:193], v[56:57], v[236:237]
	v_pk_mul_f32 v[194:195], v[50:51], v[238:239]
	v_pk_mul_f32 v[148:149], v[52:53], v[240:241]
	v_cvt_pk_bf16_f32 v134, v190, v191
	v_cvt_pk_bf16_f32 v135, v192, v193
	v_cvt_pk_bf16_f32 v136, v194, v195
	v_cvt_pk_bf16_f32 v137, v148, v149
	v_lshrrev_b32_e32 v131, 1, v173
	global_store_dwordx4 v131, v[134:137], s[30:31] offset:256
	v_xor_b32_e32 v140, 16, v207
	v_xor_b32_e32 v141, 32, v207
	v_lshlrev_b32_e32 v140, 2, v140
	v_lshlrev_b32_e32 v141, 2, v141
	ds_bpermute_b32 v132, v140, v130
	s_waitcnt lgkmcnt(0)
	v_add_f32_e32 v130, v130, v132
	ds_bpermute_b32 v132, v141, v130
	s_and_saveexec_b64 s[48:49], s[38:39]
	s_cbranch_execz .Lple_nostat_0
	s_waitcnt lgkmcnt(0)
	v_add_f32_e32 v130, v130, v132
	global_store_dword v177, v130, s[76:77]
.Lple_nostat_0:
	s_or_b64 exec, exec, s[48:49]
	s_waitcnt lgkmcnt(0)
.Lple_skip_1:
	v_add_u32_e32 v173, 0x20000, v176
	v_lshrrev_b32_e32 v133, 1, v173
	global_load_dwordx4 v[230:233], v133, s[36:37]
	global_load_dwordx4 v[234:237], v173, s[16:17]
	global_load_dwordx4 v[238:241], v173, s[16:17] offset:16
	v_mul_f32_e32 v122, v122, v185
	v_mul_f32_e32 v123, v123, v185
	v_mul_f32_e32 v124, v124, v185
	v_mul_f32_e32 v125, v125, v185
	v_mul_f32_e32 v126, v126, v185
	v_mul_f32_e32 v127, v127, v185
	v_mul_f32_e32 v128, v128, v185
	v_mul_f32_e32 v129, v129, v185
	v_mul_f32_e32 v122, 0xbfb8aa3b, v122
	v_mul_f32_e32 v123, 0xbfb8aa3b, v123
	v_mul_f32_e32 v124, 0xbfb8aa3b, v124
	v_mul_f32_e32 v125, 0xbfb8aa3b, v125
	v_mul_f32_e32 v126, 0xbfb8aa3b, v126
	v_mul_f32_e32 v127, 0xbfb8aa3b, v127
	v_mul_f32_e32 v128, 0xbfb8aa3b, v128
	v_mul_f32_e32 v129, 0xbfb8aa3b, v129
	v_exp_f32_e32 v122, v122
	v_exp_f32_e32 v123, v123
	v_exp_f32_e32 v124, v124
	v_exp_f32_e32 v125, v125
	v_exp_f32_e32 v126, v126
	v_exp_f32_e32 v127, v127
	v_exp_f32_e32 v128, v128
	v_exp_f32_e32 v129, v129
	v_add_f32_e32 v122, 1.0, v122
	v_add_f32_e32 v123, 1.0, v123
	v_add_f32_e32 v124, 1.0, v124
	v_add_f32_e32 v125, 1.0, v125
	v_add_f32_e32 v126, 1.0, v126
	v_add_f32_e32 v127, 1.0, v127
	v_add_f32_e32 v128, 1.0, v128
	v_add_f32_e32 v129, 1.0, v129
	v_rcp_f32_e32 v122, v122
	v_rcp_f32_e32 v123, v123
	v_rcp_f32_e32 v124, v124
	v_rcp_f32_e32 v125, v125
	v_rcp_f32_e32 v126, v126
	v_rcp_f32_e32 v127, v127
	v_rcp_f32_e32 v128, v128
	v_rcp_f32_e32 v129, v129
	s_waitcnt vmcnt(10)
	v_lshlrev_b32_e32 v190, 16, v242
	v_and_b32_e32 v191, 0xffff0000, v242
	v_lshlrev_b32_e32 v192, 16, v243
	v_and_b32_e32 v193, 0xffff0000, v243
	v_lshlrev_b32_e32 v194, 16, v244
	v_and_b32_e32 v195, 0xffff0000, v244
	v_lshlrev_b32_e32 v148, 16, v245
	v_and_b32_e32 v149, 0xffff0000, v245
	v_pk_fma_f32 v[246:247], v[126:127], v[190:191], v[246:247]
	v_pk_fma_f32 v[248:249], v[128:129], v[192:193], v[248:249]
	v_pk_fma_f32 v[186:187], v[122:123], v[194:195], v[186:187]
	v_pk_fma_f32 v[188:189], v[124:125], v[148:149], v[188:189]
	global_store_dwordx4 v217, v[246:249], s[16:17]
	global_store_dwordx4 v217, v[186:189], s[16:17] offset:16
	s_and_b64 vcc, exec, s[2:3]
	s_cbranch_vccnz .Lple_skip_2
	v_mul_f32_e32 v122, v247, v247
	v_mul_f32_e32 v123, v249, v249
	v_fmac_f32_e32 v122, v246, v246
	v_fmac_f32_e32 v123, v248, v248
	v_add_f32_e32 v122, v122, v123
	v_mul_f32_e32 v123, v187, v187
	v_fmac_f32_e32 v123, v186, v186
	v_add_f32_e32 v122, v123, v122
	v_mul_f32_e32 v123, v189, v189
	v_fmac_f32_e32 v123, v188, v188
	v_add_f32_e32 v122, v123, v122
	v_pk_mul_f32 v[190:191], v[62:63], v[246:247]
	v_pk_mul_f32 v[192:193], v[64:65], v[248:249]
	v_pk_mul_f32 v[194:195], v[58:59], v[186:187]
	v_pk_mul_f32 v[148:149], v[60:61], v[188:189]
	v_cvt_pk_bf16_f32 v126, v190, v191
	v_cvt_pk_bf16_f32 v127, v192, v193
	v_cvt_pk_bf16_f32 v128, v194, v195
	v_cvt_pk_bf16_f32 v129, v148, v149
	v_lshrrev_b32_e32 v124, 1, v217
	global_store_dwordx4 v124, v[126:129], s[30:31]
.Lple_skip_2:
	v_add_u32_e32 v217, 0x20000, v176
	v_lshrrev_b32_e32 v125, 1, v217
	global_load_dwordx4 v[242:245], v125, s[36:37] offset:256
	global_load_dwordx4 v[246:249], v217, s[16:17] offset:512
	global_load_dwordx4 v[186:189], v217, s[16:17] offset:528
	v_mul_f32_e32 v114, v114, v185
	v_mul_f32_e32 v115, v115, v185
	v_mul_f32_e32 v116, v116, v185
	v_mul_f32_e32 v117, v117, v185
	v_mul_f32_e32 v118, v118, v185
	v_mul_f32_e32 v119, v119, v185
	v_mul_f32_e32 v120, v120, v185
	v_mul_f32_e32 v121, v121, v185
	v_mul_f32_e32 v114, 0xbfb8aa3b, v114
	v_mul_f32_e32 v115, 0xbfb8aa3b, v115
	v_mul_f32_e32 v116, 0xbfb8aa3b, v116
	v_mul_f32_e32 v117, 0xbfb8aa3b, v117
	v_mul_f32_e32 v118, 0xbfb8aa3b, v118
	v_mul_f32_e32 v119, 0xbfb8aa3b, v119
	v_mul_f32_e32 v120, 0xbfb8aa3b, v120
	v_mul_f32_e32 v121, 0xbfb8aa3b, v121
	v_exp_f32_e32 v114, v114
	v_exp_f32_e32 v115, v115
	v_exp_f32_e32 v116, v116
	v_exp_f32_e32 v117, v117
	v_exp_f32_e32 v118, v118
	v_exp_f32_e32 v119, v119
	v_exp_f32_e32 v120, v120
	v_exp_f32_e32 v121, v121
	v_add_f32_e32 v114, 1.0, v114
	v_add_f32_e32 v115, 1.0, v115
	v_add_f32_e32 v116, 1.0, v116
	v_add_f32_e32 v117, 1.0, v117
	v_add_f32_e32 v118, 1.0, v118
	v_add_f32_e32 v119, 1.0, v119
	v_add_f32_e32 v120, 1.0, v120
	v_add_f32_e32 v121, 1.0, v121
	v_rcp_f32_e32 v114, v114
	v_rcp_f32_e32 v115, v115
	v_rcp_f32_e32 v116, v116
	v_rcp_f32_e32 v117, v117
	v_rcp_f32_e32 v118, v118
	v_rcp_f32_e32 v119, v119
	v_rcp_f32_e32 v120, v120
	v_rcp_f32_e32 v121, v121
	s_waitcnt vmcnt(10)
	v_lshlrev_b32_e32 v190, 16, v218
	v_and_b32_e32 v191, 0xffff0000, v218
	v_lshlrev_b32_e32 v192, 16, v219
	v_and_b32_e32 v193, 0xffff0000, v219
	v_lshlrev_b32_e32 v194, 16, v220
	v_and_b32_e32 v195, 0xffff0000, v220
	v_lshlrev_b32_e32 v148, 16, v221
	v_and_b32_e32 v149, 0xffff0000, v221
	v_pk_fma_f32 v[222:223], v[118:119], v[190:191], v[222:223]
	v_pk_fma_f32 v[224:225], v[120:121], v[192:193], v[224:225]
	v_pk_fma_f32 v[226:227], v[114:115], v[194:195], v[226:227]
	v_pk_fma_f32 v[228:229], v[116:117], v[148:149], v[228:229]
	global_store_dwordx4 v172, v[222:225], s[16:17] offset:512
	global_store_dwordx4 v172, v[226:229], s[16:17] offset:528
	s_and_b64 vcc, exec, s[2:3]
	s_cbranch_vccnz .Lple_skip_3
	v_mul_f32_e32 v114, v222, v222
	v_mul_f32_e32 v115, v223, v223
	v_mul_f32_e32 v116, v224, v224
	v_mul_f32_e32 v117, v225, v225
	v_add_f32_e32 v114, v114, v115
	v_add_f32_e32 v116, v116, v117
	v_mul_f32_e32 v115, v226, v226
	v_mul_f32_e32 v117, v227, v227
	v_add_f32_e32 v114, v114, v116
	v_add_f32_e32 v115, v115, v117
	v_mul_f32_e32 v116, v228, v228
	v_mul_f32_e32 v117, v229, v229
	v_add_f32_e32 v114, v115, v114
	v_add_f32_e32 v116, v116, v117
	v_add_f32_e32 v114, v116, v114
	v_add_f32_e32 v114, v122, v114
	v_pk_mul_f32 v[190:191], v[54:55], v[222:223]
	v_pk_mul_f32 v[192:193], v[56:57], v[224:225]
	v_pk_mul_f32 v[194:195], v[50:51], v[226:227]
	v_pk_mul_f32 v[148:149], v[52:53], v[228:229]
	v_cvt_pk_bf16_f32 v118, v190, v191
	v_cvt_pk_bf16_f32 v119, v192, v193
	v_cvt_pk_bf16_f32 v120, v194, v195
	v_cvt_pk_bf16_f32 v121, v148, v149
	v_lshrrev_b32_e32 v115, 1, v172
	global_store_dwordx4 v115, v[118:121], s[30:31] offset:256
	ds_bpermute_b32 v116, v140, v114
	s_waitcnt lgkmcnt(0)
	v_add_f32_e32 v114, v114, v116
	ds_bpermute_b32 v116, v141, v114
	s_and_saveexec_b64 s[48:49], s[38:39]
	s_cbranch_execz .Lple_nostat_1
	s_waitcnt lgkmcnt(0)
	v_add_f32_e32 v114, v114, v116
	global_store_dword v177, v114, s[76:77] offset:64

.Lple_skip_3:
	v_add_u32_e32 v172, 0x30000, v176
	v_lshrrev_b32_e32 v117, 1, v172
	global_load_dwordx4 v[218:221], v117, s[36:37]
	global_load_dwordx4 v[222:225], v172, s[16:17]
	global_load_dwordx4 v[226:229], v172, s[16:17] offset:16
	v_mul_f32_e32 v106, v106, v180
	v_mul_f32_e32 v107, v107, v180
	v_mul_f32_e32 v108, v108, v180
	v_mul_f32_e32 v109, v109, v180
	v_mul_f32_e32 v110, v110, v180
	v_mul_f32_e32 v111, v111, v180
	v_mul_f32_e32 v112, v112, v180
	v_mul_f32_e32 v113, v113, v180
	v_mul_f32_e32 v106, 0xbfb8aa3b, v106
	v_mul_f32_e32 v107, 0xbfb8aa3b, v107
	v_mul_f32_e32 v108, 0xbfb8aa3b, v108
	v_mul_f32_e32 v109, 0xbfb8aa3b, v109
	v_mul_f32_e32 v110, 0xbfb8aa3b, v110
	v_mul_f32_e32 v111, 0xbfb8aa3b, v111
	v_mul_f32_e32 v112, 0xbfb8aa3b, v112
	v_mul_f32_e32 v113, 0xbfb8aa3b, v113
	v_exp_f32_e32 v106, v106
	v_exp_f32_e32 v107, v107
	v_exp_f32_e32 v108, v108
	v_exp_f32_e32 v109, v109
	v_exp_f32_e32 v110, v110
	v_exp_f32_e32 v111, v111
	v_exp_f32_e32 v112, v112
	v_exp_f32_e32 v113, v113
	v_add_f32_e32 v106, 1.0, v106
	v_add_f32_e32 v107, 1.0, v107
	v_add_f32_e32 v108, 1.0, v108
	v_add_f32_e32 v109, 1.0, v109
	v_add_f32_e32 v110, 1.0, v110
	v_add_f32_e32 v111, 1.0, v111
	v_add_f32_e32 v112, 1.0, v112
	v_add_f32_e32 v113, 1.0, v113
	v_rcp_f32_e32 v106, v106
	v_rcp_f32_e32 v107, v107
	v_rcp_f32_e32 v108, v108
	v_rcp_f32_e32 v109, v109
	v_rcp_f32_e32 v110, v110
	v_rcp_f32_e32 v111, v111
	v_rcp_f32_e32 v112, v112
	v_rcp_f32_e32 v113, v113
	s_waitcnt vmcnt(10)
	v_lshlrev_b32_e32 v190, 16, v230
	v_and_b32_e32 v191, 0xffff0000, v230
	v_lshlrev_b32_e32 v192, 16, v231
	v_and_b32_e32 v193, 0xffff0000, v231
	v_lshlrev_b32_e32 v194, 16, v232
	v_and_b32_e32 v195, 0xffff0000, v232
	v_lshlrev_b32_e32 v148, 16, v233
	v_and_b32_e32 v149, 0xffff0000, v233
	v_pk_fma_f32 v[234:235], v[110:111], v[190:191], v[234:235]
	v_pk_fma_f32 v[236:237], v[112:113], v[192:193], v[236:237]
	v_pk_fma_f32 v[238:239], v[106:107], v[194:195], v[238:239]
	v_pk_fma_f32 v[240:241], v[108:109], v[148:149], v[240:241]
	global_store_dwordx4 v173, v[234:237], s[16:17]
	global_store_dwordx4 v173, v[238:241], s[16:17] offset:16
	s_and_b64 vcc, exec, s[2:3]
	s_cbranch_vccnz .Lple_skip_4
	v_mul_f32_e32 v106, v235, v235
	v_mul_f32_e32 v107, v237, v237
	v_fmac_f32_e32 v106, v234, v234
	v_fmac_f32_e32 v107, v236, v236
	v_add_f32_e32 v106, v106, v107
	v_mul_f32_e32 v107, v239, v239
	v_fmac_f32_e32 v107, v238, v238
	v_add_f32_e32 v106, v107, v106
	v_mul_f32_e32 v107, v241, v241
	v_fmac_f32_e32 v107, v240, v240
	v_add_f32_e32 v106, v107, v106
	v_pk_mul_f32 v[190:191], v[62:63], v[234:235]
	v_pk_mul_f32 v[192:193], v[64:65], v[236:237]
	v_pk_mul_f32 v[194:195], v[58:59], v[238:239]
	v_pk_mul_f32 v[148:149], v[60:61], v[240:241]
	v_cvt_pk_bf16_f32 v110, v190, v191
	v_cvt_pk_bf16_f32 v111, v192, v193
	v_cvt_pk_bf16_f32 v112, v194, v195
	v_cvt_pk_bf16_f32 v113, v148, v149
	v_lshrrev_b32_e32 v108, 1, v173
	global_store_dwordx4 v108, v[110:113], s[30:31]
.Lple_skip_4:
	v_add_u32_e32 v173, 0x30000, v176
	v_lshrrev_b32_e32 v109, 1, v173
	global_load_dwordx4 v[230:233], v109, s[36:37] offset:256
	global_load_dwordx4 v[234:237], v173, s[16:17] offset:512
	global_load_dwordx4 v[238:241], v173, s[16:17] offset:528
	v_mul_f32_e32 v98, v98, v180
	v_mul_f32_e32 v99, v99, v180
	v_mul_f32_e32 v100, v100, v180
	v_mul_f32_e32 v101, v101, v180
	v_mul_f32_e32 v102, v102, v180
	v_mul_f32_e32 v103, v103, v180
	v_mul_f32_e32 v104, v104, v180
	v_mul_f32_e32 v105, v105, v180
	v_mul_f32_e32 v98, 0xbfb8aa3b, v98
	v_mul_f32_e32 v99, 0xbfb8aa3b, v99
	v_mul_f32_e32 v100, 0xbfb8aa3b, v100
	v_mul_f32_e32 v101, 0xbfb8aa3b, v101
	v_mul_f32_e32 v102, 0xbfb8aa3b, v102
	v_mul_f32_e32 v103, 0xbfb8aa3b, v103
	v_mul_f32_e32 v104, 0xbfb8aa3b, v104
	v_mul_f32_e32 v105, 0xbfb8aa3b, v105
	v_exp_f32_e32 v98, v98
	v_exp_f32_e32 v99, v99
	v_exp_f32_e32 v100, v100
	v_exp_f32_e32 v101, v101
	v_exp_f32_e32 v102, v102
	v_exp_f32_e32 v103, v103
	v_exp_f32_e32 v104, v104
	v_exp_f32_e32 v105, v105
	v_add_f32_e32 v98, 1.0, v98
	v_add_f32_e32 v99, 1.0, v99
	v_add_f32_e32 v100, 1.0, v100
	v_add_f32_e32 v101, 1.0, v101
	v_add_f32_e32 v102, 1.0, v102
	v_add_f32_e32 v103, 1.0, v103
	v_add_f32_e32 v104, 1.0, v104
	v_add_f32_e32 v105, 1.0, v105
	v_rcp_f32_e32 v98, v98
	v_rcp_f32_e32 v99, v99
	v_rcp_f32_e32 v100, v100
	v_rcp_f32_e32 v101, v101
	v_rcp_f32_e32 v102, v102
	v_rcp_f32_e32 v103, v103
	v_rcp_f32_e32 v104, v104
	v_rcp_f32_e32 v105, v105
	s_waitcnt vmcnt(10)
	v_lshlrev_b32_e32 v190, 16, v242
	v_and_b32_e32 v191, 0xffff0000, v242
	v_lshlrev_b32_e32 v192, 16, v243
	v_and_b32_e32 v193, 0xffff0000, v243
	v_lshlrev_b32_e32 v194, 16, v244
	v_and_b32_e32 v195, 0xffff0000, v244
	v_lshlrev_b32_e32 v148, 16, v245
	v_and_b32_e32 v149, 0xffff0000, v245
	v_pk_fma_f32 v[246:247], v[102:103], v[190:191], v[246:247]
	v_pk_fma_f32 v[248:249], v[104:105], v[192:193], v[248:249]
	v_pk_fma_f32 v[186:187], v[98:99], v[194:195], v[186:187]
	v_pk_fma_f32 v[188:189], v[100:101], v[148:149], v[188:189]
	global_store_dwordx4 v217, v[246:249], s[16:17] offset:512
	global_store_dwordx4 v217, v[186:189], s[16:17] offset:528
	s_and_b64 vcc, exec, s[2:3]
	s_cbranch_vccnz .Lple_skip_5
	v_mul_f32_e32 v98, v246, v246
	v_mul_f32_e32 v99, v247, v247
	v_mul_f32_e32 v100, v248, v248
	v_mul_f32_e32 v101, v249, v249
	v_add_f32_e32 v98, v98, v99
	v_add_f32_e32 v100, v100, v101
	v_mul_f32_e32 v99, v186, v186
	v_mul_f32_e32 v101, v187, v187
	v_add_f32_e32 v98, v98, v100
	v_add_f32_e32 v99, v99, v101
	v_mul_f32_e32 v100, v188, v188
	v_mul_f32_e32 v101, v189, v189
	v_add_f32_e32 v98, v99, v98
	v_add_f32_e32 v100, v100, v101
	v_add_f32_e32 v98, v100, v98
	v_add_f32_e32 v98, v106, v98
	v_pk_mul_f32 v[190:191], v[54:55], v[246:247]
	v_pk_mul_f32 v[192:193], v[56:57], v[248:249]
	v_pk_mul_f32 v[194:195], v[50:51], v[186:187]
	v_pk_mul_f32 v[148:149], v[52:53], v[188:189]
	v_cvt_pk_bf16_f32 v102, v190, v191
	v_cvt_pk_bf16_f32 v103, v192, v193
	v_cvt_pk_bf16_f32 v104, v194, v195
	v_cvt_pk_bf16_f32 v105, v148, v149
	v_lshrrev_b32_e32 v99, 1, v217
	global_store_dwordx4 v99, v[102:105], s[30:31] offset:256
	ds_bpermute_b32 v100, v140, v98
	s_waitcnt lgkmcnt(0)
	v_add_f32_e32 v98, v98, v100
	ds_bpermute_b32 v100, v141, v98
	s_and_saveexec_b64 s[48:49], s[38:39]
	s_cbranch_execz .Lple_nostat_2
	s_waitcnt lgkmcnt(0)
	v_add_f32_e32 v98, v98, v100
	global_store_dword v177, v98, s[76:77] offset:128

.Lple_skip_5:
	v_add_u32_e32 v217, 0x80000, v176
	v_lshrrev_b32_e32 v101, 1, v217
	global_load_dwordx4 v[242:245], v101, s[36:37]
	global_load_dwordx4 v[246:249], v217, s[16:17]
	global_load_dwordx4 v[186:189], v217, s[16:17] offset:16
	v_mul_f32_e32 v90, v90, v181
	v_mul_f32_e32 v91, v91, v181
	v_mul_f32_e32 v92, v92, v181
	v_mul_f32_e32 v93, v93, v181
	v_mul_f32_e32 v94, v94, v181
	v_mul_f32_e32 v95, v95, v181
	v_mul_f32_e32 v96, v96, v181
	v_mul_f32_e32 v97, v97, v181
	v_mul_f32_e32 v90, 0xbfb8aa3b, v90
	v_mul_f32_e32 v91, 0xbfb8aa3b, v91
	v_mul_f32_e32 v92, 0xbfb8aa3b, v92
	v_mul_f32_e32 v93, 0xbfb8aa3b, v93
	v_mul_f32_e32 v94, 0xbfb8aa3b, v94
	v_mul_f32_e32 v95, 0xbfb8aa3b, v95
	v_mul_f32_e32 v96, 0xbfb8aa3b, v96
	v_mul_f32_e32 v97, 0xbfb8aa3b, v97
	v_exp_f32_e32 v90, v90
	v_exp_f32_e32 v91, v91
	v_exp_f32_e32 v92, v92
	v_exp_f32_e32 v93, v93
	v_exp_f32_e32 v94, v94
	v_exp_f32_e32 v95, v95
	v_exp_f32_e32 v96, v96
	v_exp_f32_e32 v97, v97
	v_add_f32_e32 v90, 1.0, v90
	v_add_f32_e32 v91, 1.0, v91
	v_add_f32_e32 v92, 1.0, v92
	v_add_f32_e32 v93, 1.0, v93
	v_add_f32_e32 v94, 1.0, v94
	v_add_f32_e32 v95, 1.0, v95
	v_add_f32_e32 v96, 1.0, v96
	v_add_f32_e32 v97, 1.0, v97
	v_rcp_f32_e32 v90, v90
	v_rcp_f32_e32 v91, v91
	v_rcp_f32_e32 v92, v92
	v_rcp_f32_e32 v93, v93
	v_rcp_f32_e32 v94, v94
	v_rcp_f32_e32 v95, v95
	v_rcp_f32_e32 v96, v96
	v_rcp_f32_e32 v97, v97
	s_waitcnt vmcnt(10)
	v_lshlrev_b32_e32 v190, 16, v218
	v_and_b32_e32 v191, 0xffff0000, v218
	v_lshlrev_b32_e32 v192, 16, v219
	v_and_b32_e32 v193, 0xffff0000, v219
	v_lshlrev_b32_e32 v194, 16, v220
	v_and_b32_e32 v195, 0xffff0000, v220
	v_lshlrev_b32_e32 v148, 16, v221
	v_and_b32_e32 v149, 0xffff0000, v221
	v_pk_fma_f32 v[222:223], v[94:95], v[190:191], v[222:223]
	v_pk_fma_f32 v[224:225], v[96:97], v[192:193], v[224:225]
	v_pk_fma_f32 v[226:227], v[90:91], v[194:195], v[226:227]
	v_pk_fma_f32 v[228:229], v[92:93], v[148:149], v[228:229]
	global_store_dwordx4 v172, v[222:225], s[16:17]
	global_store_dwordx4 v172, v[226:229], s[16:17] offset:16
	s_and_b64 vcc, exec, s[2:3]
	s_cbranch_vccnz .Lple_skip_6
	v_mul_f32_e32 v90, v223, v223
	v_mul_f32_e32 v91, v225, v225
	v_fmac_f32_e32 v90, v222, v222
	v_fmac_f32_e32 v91, v224, v224
	v_add_f32_e32 v90, v90, v91
	v_mul_f32_e32 v91, v227, v227
	v_fmac_f32_e32 v91, v226, v226
	v_add_f32_e32 v90, v91, v90
	v_mul_f32_e32 v91, v229, v229
	v_fmac_f32_e32 v91, v228, v228
	v_add_f32_e32 v90, v91, v90
	v_pk_mul_f32 v[190:191], v[62:63], v[222:223]
	v_pk_mul_f32 v[192:193], v[64:65], v[224:225]
	v_pk_mul_f32 v[194:195], v[58:59], v[226:227]
	v_pk_mul_f32 v[148:149], v[60:61], v[228:229]
	v_cvt_pk_bf16_f32 v94, v190, v191
	v_cvt_pk_bf16_f32 v95, v192, v193
	v_cvt_pk_bf16_f32 v96, v194, v195
	v_cvt_pk_bf16_f32 v97, v148, v149
	v_lshrrev_b32_e32 v92, 1, v172
	global_store_dwordx4 v92, v[94:97], s[30:31]
.Lple_skip_6:
	v_add_u32_e32 v172, 0x80000, v176
	v_lshrrev_b32_e32 v93, 1, v172
	global_load_dwordx4 v[218:221], v93, s[36:37] offset:256
	global_load_dwordx4 v[222:225], v172, s[16:17] offset:512
	global_load_dwordx4 v[226:229], v172, s[16:17] offset:528
	v_mul_f32_e32 v82, v82, v181
	v_mul_f32_e32 v83, v83, v181
	v_mul_f32_e32 v84, v84, v181
	v_mul_f32_e32 v85, v85, v181
	v_mul_f32_e32 v86, v86, v181
	v_mul_f32_e32 v87, v87, v181
	v_mul_f32_e32 v88, v88, v181
	v_mul_f32_e32 v89, v89, v181
	v_mul_f32_e32 v82, 0xbfb8aa3b, v82
	v_mul_f32_e32 v83, 0xbfb8aa3b, v83
	v_mul_f32_e32 v84, 0xbfb8aa3b, v84
	v_mul_f32_e32 v85, 0xbfb8aa3b, v85
	v_mul_f32_e32 v86, 0xbfb8aa3b, v86
	v_mul_f32_e32 v87, 0xbfb8aa3b, v87
	v_mul_f32_e32 v88, 0xbfb8aa3b, v88
	v_mul_f32_e32 v89, 0xbfb8aa3b, v89
	v_exp_f32_e32 v82, v82
	v_exp_f32_e32 v83, v83
	v_exp_f32_e32 v84, v84
	v_exp_f32_e32 v85, v85
	v_exp_f32_e32 v86, v86
	v_exp_f32_e32 v87, v87
	v_exp_f32_e32 v88, v88
	v_exp_f32_e32 v89, v89
	v_add_f32_e32 v82, 1.0, v82
	v_add_f32_e32 v83, 1.0, v83
	v_add_f32_e32 v84, 1.0, v84
	v_add_f32_e32 v85, 1.0, v85
	v_add_f32_e32 v86, 1.0, v86
	v_add_f32_e32 v87, 1.0, v87
	v_add_f32_e32 v88, 1.0, v88
	v_add_f32_e32 v89, 1.0, v89
	v_rcp_f32_e32 v82, v82
	v_rcp_f32_e32 v83, v83
	v_rcp_f32_e32 v84, v84
	v_rcp_f32_e32 v85, v85
	v_rcp_f32_e32 v86, v86
	v_rcp_f32_e32 v87, v87
	v_rcp_f32_e32 v88, v88
	v_rcp_f32_e32 v89, v89
	s_waitcnt vmcnt(10)
	v_lshlrev_b32_e32 v190, 16, v230
	v_and_b32_e32 v191, 0xffff0000, v230
	v_lshlrev_b32_e32 v192, 16, v231
	v_and_b32_e32 v193, 0xffff0000, v231
	v_lshlrev_b32_e32 v194, 16, v232
	v_and_b32_e32 v195, 0xffff0000, v232
	v_lshlrev_b32_e32 v148, 16, v233
	v_and_b32_e32 v149, 0xffff0000, v233
	v_pk_fma_f32 v[234:235], v[86:87], v[190:191], v[234:235]
	v_pk_fma_f32 v[236:237], v[88:89], v[192:193], v[236:237]
	v_pk_fma_f32 v[238:239], v[82:83], v[194:195], v[238:239]
	v_pk_fma_f32 v[240:241], v[84:85], v[148:149], v[240:241]
	global_store_dwordx4 v173, v[234:237], s[16:17] offset:512
	global_store_dwordx4 v173, v[238:241], s[16:17] offset:528
	s_and_b64 vcc, exec, s[2:3]
	s_cbranch_vccnz .Lple_skip_7
	v_mul_f32_e32 v82, v234, v234
	v_mul_f32_e32 v83, v235, v235
	v_mul_f32_e32 v84, v236, v236
	v_mul_f32_e32 v85, v237, v237
	v_add_f32_e32 v82, v82, v83
	v_add_f32_e32 v84, v84, v85
	v_mul_f32_e32 v83, v238, v238
	v_mul_f32_e32 v85, v239, v239
	v_add_f32_e32 v82, v82, v84
	v_add_f32_e32 v83, v83, v85
	v_mul_f32_e32 v84, v240, v240
	v_mul_f32_e32 v85, v241, v241
	v_add_f32_e32 v82, v83, v82
	v_add_f32_e32 v84, v84, v85
	v_add_f32_e32 v82, v84, v82
	v_add_f32_e32 v82, v90, v82
	v_pk_mul_f32 v[190:191], v[54:55], v[234:235]
	v_pk_mul_f32 v[192:193], v[56:57], v[236:237]
	v_pk_mul_f32 v[194:195], v[50:51], v[238:239]
	v_pk_mul_f32 v[148:149], v[52:53], v[240:241]
	v_cvt_pk_bf16_f32 v86, v190, v191
	v_cvt_pk_bf16_f32 v87, v192, v193
	v_cvt_pk_bf16_f32 v88, v194, v195
	v_cvt_pk_bf16_f32 v89, v148, v149
	v_lshrrev_b32_e32 v83, 1, v173
	global_store_dwordx4 v83, v[86:89], s[30:31] offset:256
	ds_bpermute_b32 v84, v140, v82
	s_waitcnt lgkmcnt(0)
	v_add_f32_e32 v82, v82, v84
	ds_bpermute_b32 v84, v141, v82
	s_and_saveexec_b64 s[48:49], s[38:39]
	s_cbranch_execz .Lple_nostat_3
	s_waitcnt lgkmcnt(0)
	v_add_f32_e32 v82, v82, v84
	global_store_dword v177, v82, s[76:77] offset:192

.Lple_skip_7:
	v_add_u32_e32 v173, 0x90000, v176
	v_lshrrev_b32_e32 v85, 1, v173
	global_load_dwordx4 v[230:233], v85, s[36:37]
	global_load_dwordx4 v[234:237], v173, s[16:17]
	global_load_dwordx4 v[238:241], v173, s[16:17] offset:16
	v_mul_f32_e32 v74, v74, v178
	v_mul_f32_e32 v75, v75, v178
	v_mul_f32_e32 v76, v76, v178
	v_mul_f32_e32 v77, v77, v178
	v_mul_f32_e32 v78, v78, v178
	v_mul_f32_e32 v79, v79, v178
	v_mul_f32_e32 v80, v80, v178
	v_mul_f32_e32 v81, v81, v178
	v_mul_f32_e32 v74, 0xbfb8aa3b, v74
	v_mul_f32_e32 v75, 0xbfb8aa3b, v75
	v_mul_f32_e32 v76, 0xbfb8aa3b, v76
	v_mul_f32_e32 v77, 0xbfb8aa3b, v77
	v_mul_f32_e32 v78, 0xbfb8aa3b, v78
	v_mul_f32_e32 v79, 0xbfb8aa3b, v79
	v_mul_f32_e32 v80, 0xbfb8aa3b, v80
	v_mul_f32_e32 v81, 0xbfb8aa3b, v81
	v_exp_f32_e32 v74, v74
	v_exp_f32_e32 v75, v75
	v_exp_f32_e32 v76, v76
	v_exp_f32_e32 v77, v77
	v_exp_f32_e32 v78, v78
	v_exp_f32_e32 v79, v79
	v_exp_f32_e32 v80, v80
	v_exp_f32_e32 v81, v81
	v_add_f32_e32 v74, 1.0, v74
	v_add_f32_e32 v75, 1.0, v75
	v_add_f32_e32 v76, 1.0, v76
	v_add_f32_e32 v77, 1.0, v77
	v_add_f32_e32 v78, 1.0, v78
	v_add_f32_e32 v79, 1.0, v79
	v_add_f32_e32 v80, 1.0, v80
	v_add_f32_e32 v81, 1.0, v81
	v_rcp_f32_e32 v74, v74
	v_rcp_f32_e32 v75, v75
	v_rcp_f32_e32 v76, v76
	v_rcp_f32_e32 v77, v77
	v_rcp_f32_e32 v78, v78
	v_rcp_f32_e32 v79, v79
	v_rcp_f32_e32 v80, v80
	v_rcp_f32_e32 v81, v81
	s_waitcnt vmcnt(10)
	v_lshlrev_b32_e32 v190, 16, v242
	v_and_b32_e32 v191, 0xffff0000, v242
	v_lshlrev_b32_e32 v192, 16, v243
	v_and_b32_e32 v193, 0xffff0000, v243
	v_lshlrev_b32_e32 v194, 16, v244
	v_and_b32_e32 v195, 0xffff0000, v244
	v_lshlrev_b32_e32 v148, 16, v245
	v_and_b32_e32 v149, 0xffff0000, v245
	v_pk_fma_f32 v[246:247], v[78:79], v[190:191], v[246:247]
	v_pk_fma_f32 v[248:249], v[80:81], v[192:193], v[248:249]
	v_pk_fma_f32 v[186:187], v[74:75], v[194:195], v[186:187]
	v_pk_fma_f32 v[188:189], v[76:77], v[148:149], v[188:189]
	global_store_dwordx4 v217, v[246:249], s[16:17]
	global_store_dwordx4 v217, v[186:189], s[16:17] offset:16
	s_and_b64 vcc, exec, s[2:3]
	s_cbranch_vccnz .Lple_skip_8
	v_mul_f32_e32 v74, v247, v247
	v_mul_f32_e32 v75, v249, v249
	v_fmac_f32_e32 v74, v246, v246
	v_fmac_f32_e32 v75, v248, v248
	v_add_f32_e32 v74, v74, v75
	v_mul_f32_e32 v75, v187, v187
	v_fmac_f32_e32 v75, v186, v186
	v_add_f32_e32 v74, v75, v74
	v_mul_f32_e32 v75, v189, v189
	v_fmac_f32_e32 v75, v188, v188
	v_add_f32_e32 v74, v75, v74
	v_pk_mul_f32 v[190:191], v[62:63], v[246:247]
	v_pk_mul_f32 v[192:193], v[64:65], v[248:249]
	v_pk_mul_f32 v[194:195], v[58:59], v[186:187]
	v_pk_mul_f32 v[148:149], v[60:61], v[188:189]
	v_cvt_pk_bf16_f32 v78, v190, v191
	v_cvt_pk_bf16_f32 v79, v192, v193
	v_cvt_pk_bf16_f32 v80, v194, v195
	v_cvt_pk_bf16_f32 v81, v148, v149
	v_lshrrev_b32_e32 v76, 1, v217
	global_store_dwordx4 v76, v[78:81], s[30:31]
.Lple_skip_8:
	v_add_u32_e32 v217, 0x90000, v176
	v_lshrrev_b32_e32 v77, 1, v217
	global_load_dwordx4 v[242:245], v77, s[36:37] offset:256
	global_load_dwordx4 v[246:249], v217, s[16:17] offset:512
	global_load_dwordx4 v[186:189], v217, s[16:17] offset:528
	v_mul_f32_e32 v66, v66, v178
	v_mul_f32_e32 v67, v67, v178
	v_mul_f32_e32 v68, v68, v178
	v_mul_f32_e32 v69, v69, v178
	v_mul_f32_e32 v70, v70, v178
	v_mul_f32_e32 v71, v71, v178
	v_mul_f32_e32 v72, v72, v178
	v_mul_f32_e32 v73, v73, v178
	v_mul_f32_e32 v66, 0xbfb8aa3b, v66
	v_mul_f32_e32 v67, 0xbfb8aa3b, v67
	v_mul_f32_e32 v68, 0xbfb8aa3b, v68
	v_mul_f32_e32 v69, 0xbfb8aa3b, v69
	v_mul_f32_e32 v70, 0xbfb8aa3b, v70
	v_mul_f32_e32 v71, 0xbfb8aa3b, v71
	v_mul_f32_e32 v72, 0xbfb8aa3b, v72
	v_mul_f32_e32 v73, 0xbfb8aa3b, v73
	v_exp_f32_e32 v66, v66
	v_exp_f32_e32 v67, v67
	v_exp_f32_e32 v68, v68
	v_exp_f32_e32 v69, v69
	v_exp_f32_e32 v70, v70
	v_exp_f32_e32 v71, v71
	v_exp_f32_e32 v72, v72
	v_exp_f32_e32 v73, v73
	v_add_f32_e32 v66, 1.0, v66
	v_add_f32_e32 v67, 1.0, v67
	v_add_f32_e32 v68, 1.0, v68
	v_add_f32_e32 v69, 1.0, v69
	v_add_f32_e32 v70, 1.0, v70
	v_add_f32_e32 v71, 1.0, v71
	v_add_f32_e32 v72, 1.0, v72
	v_add_f32_e32 v73, 1.0, v73
	v_rcp_f32_e32 v66, v66
	v_rcp_f32_e32 v67, v67
	v_rcp_f32_e32 v68, v68
	v_rcp_f32_e32 v69, v69
	v_rcp_f32_e32 v70, v70
	v_rcp_f32_e32 v71, v71
	v_rcp_f32_e32 v72, v72
	v_rcp_f32_e32 v73, v73
	s_waitcnt vmcnt(10)
	v_lshlrev_b32_e32 v190, 16, v218
	v_and_b32_e32 v191, 0xffff0000, v218
	v_lshlrev_b32_e32 v192, 16, v219
	v_and_b32_e32 v193, 0xffff0000, v219
	v_lshlrev_b32_e32 v194, 16, v220
	v_and_b32_e32 v195, 0xffff0000, v220
	v_lshlrev_b32_e32 v148, 16, v221
	v_and_b32_e32 v149, 0xffff0000, v221
	v_pk_fma_f32 v[222:223], v[70:71], v[190:191], v[222:223]
	v_pk_fma_f32 v[224:225], v[72:73], v[192:193], v[224:225]
	v_pk_fma_f32 v[226:227], v[66:67], v[194:195], v[226:227]
	v_pk_fma_f32 v[228:229], v[68:69], v[148:149], v[228:229]
	global_store_dwordx4 v172, v[222:225], s[16:17] offset:512
	global_store_dwordx4 v172, v[226:229], s[16:17] offset:528
	s_and_b64 vcc, exec, s[2:3]
	s_cbranch_vccnz .Lple_skip_9
	v_mul_f32_e32 v66, v222, v222
	v_mul_f32_e32 v67, v223, v223
	v_mul_f32_e32 v68, v224, v224
	v_mul_f32_e32 v69, v225, v225
	v_add_f32_e32 v66, v66, v67
	v_add_f32_e32 v68, v68, v69
	v_mul_f32_e32 v67, v226, v226
	v_mul_f32_e32 v69, v227, v227
	v_add_f32_e32 v66, v66, v68
	v_add_f32_e32 v67, v67, v69
	v_mul_f32_e32 v68, v228, v228
	v_mul_f32_e32 v69, v229, v229
	v_add_f32_e32 v66, v67, v66
	v_add_f32_e32 v68, v68, v69
	v_add_f32_e32 v66, v68, v66
	v_add_f32_e32 v66, v74, v66
	v_pk_mul_f32 v[190:191], v[54:55], v[222:223]
	v_pk_mul_f32 v[192:193], v[56:57], v[224:225]
	v_pk_mul_f32 v[194:195], v[50:51], v[226:227]
	v_pk_mul_f32 v[148:149], v[52:53], v[228:229]
	v_cvt_pk_bf16_f32 v70, v190, v191
	v_cvt_pk_bf16_f32 v71, v192, v193
	v_cvt_pk_bf16_f32 v72, v194, v195
	v_cvt_pk_bf16_f32 v73, v148, v149
	v_lshrrev_b32_e32 v67, 1, v172
	global_store_dwordx4 v67, v[70:73], s[30:31] offset:256
	ds_bpermute_b32 v68, v140, v66
	s_waitcnt lgkmcnt(0)
	v_add_f32_e32 v66, v66, v68
	ds_bpermute_b32 v68, v141, v66
	s_and_saveexec_b64 s[48:49], s[38:39]
	s_cbranch_execz .Lple_nostat_4
	s_waitcnt lgkmcnt(0)
	v_add_f32_e32 v66, v66, v68
	global_store_dword v177, v66, s[76:77] offset:512

.Lple_skip_9:
	v_add_u32_e32 v172, 0xa0000, v176
	v_lshrrev_b32_e32 v69, 1, v172
	global_load_dwordx4 v[218:221], v69, s[36:37]
	global_load_dwordx4 v[222:225], v172, s[16:17]
	global_load_dwordx4 v[226:229], v172, s[16:17] offset:16
	v_mul_f32_e32 v42, v42, v179
	v_mul_f32_e32 v43, v43, v179
	v_mul_f32_e32 v44, v44, v179
	v_mul_f32_e32 v45, v45, v179
	v_mul_f32_e32 v46, v46, v179
	v_mul_f32_e32 v47, v47, v179
	v_mul_f32_e32 v48, v48, v179
	v_mul_f32_e32 v49, v49, v179
	v_mul_f32_e32 v42, 0xbfb8aa3b, v42
	v_mul_f32_e32 v43, 0xbfb8aa3b, v43
	v_mul_f32_e32 v44, 0xbfb8aa3b, v44
	v_mul_f32_e32 v45, 0xbfb8aa3b, v45
	v_mul_f32_e32 v46, 0xbfb8aa3b, v46
	v_mul_f32_e32 v47, 0xbfb8aa3b, v47
	v_mul_f32_e32 v48, 0xbfb8aa3b, v48
	v_mul_f32_e32 v49, 0xbfb8aa3b, v49
	v_exp_f32_e32 v42, v42
	v_exp_f32_e32 v43, v43
	v_exp_f32_e32 v44, v44
	v_exp_f32_e32 v45, v45
	v_exp_f32_e32 v46, v46
	v_exp_f32_e32 v47, v47
	v_exp_f32_e32 v48, v48
	v_exp_f32_e32 v49, v49
	v_add_f32_e32 v42, 1.0, v42
	v_add_f32_e32 v43, 1.0, v43
	v_add_f32_e32 v44, 1.0, v44
	v_add_f32_e32 v45, 1.0, v45
	v_add_f32_e32 v46, 1.0, v46
	v_add_f32_e32 v47, 1.0, v47
	v_add_f32_e32 v48, 1.0, v48
	v_add_f32_e32 v49, 1.0, v49
	v_rcp_f32_e32 v42, v42
	v_rcp_f32_e32 v43, v43
	v_rcp_f32_e32 v44, v44
	v_rcp_f32_e32 v45, v45
	v_rcp_f32_e32 v46, v46
	v_rcp_f32_e32 v47, v47
	v_rcp_f32_e32 v48, v48
	v_rcp_f32_e32 v49, v49
	s_waitcnt vmcnt(10)
	v_lshlrev_b32_e32 v190, 16, v230
	v_and_b32_e32 v191, 0xffff0000, v230
	v_lshlrev_b32_e32 v192, 16, v231
	v_and_b32_e32 v193, 0xffff0000, v231
	v_lshlrev_b32_e32 v194, 16, v232
	v_and_b32_e32 v195, 0xffff0000, v232
	v_lshlrev_b32_e32 v148, 16, v233
	v_and_b32_e32 v149, 0xffff0000, v233
	v_pk_fma_f32 v[234:235], v[46:47], v[190:191], v[234:235]
	v_pk_fma_f32 v[236:237], v[48:49], v[192:193], v[236:237]
	v_pk_fma_f32 v[238:239], v[42:43], v[194:195], v[238:239]
	v_pk_fma_f32 v[240:241], v[44:45], v[148:149], v[240:241]
	global_store_dwordx4 v173, v[234:237], s[16:17]
	global_store_dwordx4 v173, v[238:241], s[16:17] offset:16
	s_and_b64 vcc, exec, s[2:3]
	s_cbranch_vccnz .Lple_skip_10
	v_mul_f32_e32 v42, v235, v235
	v_mul_f32_e32 v43, v237, v237
	v_fmac_f32_e32 v42, v234, v234
	v_fmac_f32_e32 v43, v236, v236
	v_add_f32_e32 v42, v42, v43
	v_mul_f32_e32 v43, v239, v239
	v_fmac_f32_e32 v43, v238, v238
	v_add_f32_e32 v42, v43, v42
	v_mul_f32_e32 v43, v241, v241
	v_fmac_f32_e32 v43, v240, v240
	v_add_f32_e32 v42, v43, v42
	v_pk_mul_f32 v[190:191], v[62:63], v[234:235]
	v_pk_mul_f32 v[192:193], v[64:65], v[236:237]
	v_pk_mul_f32 v[194:195], v[58:59], v[238:239]
	v_pk_mul_f32 v[148:149], v[60:61], v[240:241]
	v_cvt_pk_bf16_f32 v46, v190, v191
	v_cvt_pk_bf16_f32 v47, v192, v193
	v_cvt_pk_bf16_f32 v48, v194, v195
	v_cvt_pk_bf16_f32 v49, v148, v149
	v_lshrrev_b32_e32 v44, 1, v173
	global_store_dwordx4 v44, v[46:49], s[30:31]
.Lple_skip_10:
	v_add_u32_e32 v173, 0xa0000, v176
	v_lshrrev_b32_e32 v45, 1, v173
	global_load_dwordx4 v[230:233], v45, s[36:37] offset:256
	global_load_dwordx4 v[234:237], v173, s[16:17] offset:512
	global_load_dwordx4 v[238:241], v173, s[16:17] offset:528
	v_mul_f32_e32 v34, v34, v179
	v_mul_f32_e32 v35, v35, v179
	v_mul_f32_e32 v36, v36, v179
	v_mul_f32_e32 v37, v37, v179
	v_mul_f32_e32 v38, v38, v179
	v_mul_f32_e32 v39, v39, v179
	v_mul_f32_e32 v40, v40, v179
	v_mul_f32_e32 v41, v41, v179
	v_mul_f32_e32 v34, 0xbfb8aa3b, v34
	v_mul_f32_e32 v35, 0xbfb8aa3b, v35
	v_mul_f32_e32 v36, 0xbfb8aa3b, v36
	v_mul_f32_e32 v37, 0xbfb8aa3b, v37
	v_mul_f32_e32 v38, 0xbfb8aa3b, v38
	v_mul_f32_e32 v39, 0xbfb8aa3b, v39
	v_mul_f32_e32 v40, 0xbfb8aa3b, v40
	v_mul_f32_e32 v41, 0xbfb8aa3b, v41
	v_exp_f32_e32 v34, v34
	v_exp_f32_e32 v35, v35
	v_exp_f32_e32 v36, v36
	v_exp_f32_e32 v37, v37
	v_exp_f32_e32 v38, v38
	v_exp_f32_e32 v39, v39
	v_exp_f32_e32 v40, v40
	v_exp_f32_e32 v41, v41
	v_add_f32_e32 v34, 1.0, v34
	v_add_f32_e32 v35, 1.0, v35
	v_add_f32_e32 v36, 1.0, v36
	v_add_f32_e32 v37, 1.0, v37
	v_add_f32_e32 v38, 1.0, v38
	v_add_f32_e32 v39, 1.0, v39
	v_add_f32_e32 v40, 1.0, v40
	v_add_f32_e32 v41, 1.0, v41
	v_rcp_f32_e32 v34, v34
	v_rcp_f32_e32 v35, v35
	v_rcp_f32_e32 v36, v36
	v_rcp_f32_e32 v37, v37
	v_rcp_f32_e32 v38, v38
	v_rcp_f32_e32 v39, v39
	v_rcp_f32_e32 v40, v40
	v_rcp_f32_e32 v41, v41
	s_waitcnt vmcnt(10)
	v_lshlrev_b32_e32 v190, 16, v242
	v_and_b32_e32 v191, 0xffff0000, v242
	v_lshlrev_b32_e32 v192, 16, v243
	v_and_b32_e32 v193, 0xffff0000, v243
	v_lshlrev_b32_e32 v194, 16, v244
	v_and_b32_e32 v195, 0xffff0000, v244
	v_lshlrev_b32_e32 v148, 16, v245
	v_and_b32_e32 v149, 0xffff0000, v245
	v_pk_fma_f32 v[246:247], v[38:39], v[190:191], v[246:247]
	v_pk_fma_f32 v[248:249], v[40:41], v[192:193], v[248:249]
	v_pk_fma_f32 v[186:187], v[34:35], v[194:195], v[186:187]
	v_pk_fma_f32 v[188:189], v[36:37], v[148:149], v[188:189]
	global_store_dwordx4 v217, v[246:249], s[16:17] offset:512
	global_store_dwordx4 v217, v[186:189], s[16:17] offset:528
	s_and_b64 vcc, exec, s[2:3]
	s_cbranch_vccnz .Lple_skip_11
	v_mul_f32_e32 v34, v246, v246
	v_mul_f32_e32 v35, v247, v247
	v_mul_f32_e32 v36, v248, v248
	v_mul_f32_e32 v37, v249, v249
	v_add_f32_e32 v34, v34, v35
	v_add_f32_e32 v36, v36, v37
	v_mul_f32_e32 v35, v186, v186
	v_mul_f32_e32 v37, v187, v187
	v_add_f32_e32 v34, v34, v36
	v_add_f32_e32 v35, v35, v37
	v_mul_f32_e32 v36, v188, v188
	v_mul_f32_e32 v37, v189, v189
	v_add_f32_e32 v34, v35, v34
	v_add_f32_e32 v36, v36, v37
	v_add_f32_e32 v34, v36, v34
	v_add_f32_e32 v34, v42, v34
	v_pk_mul_f32 v[190:191], v[54:55], v[246:247]
	v_pk_mul_f32 v[192:193], v[56:57], v[248:249]
	v_pk_mul_f32 v[194:195], v[50:51], v[186:187]
	v_pk_mul_f32 v[148:149], v[52:53], v[188:189]
	v_cvt_pk_bf16_f32 v38, v190, v191
	v_cvt_pk_bf16_f32 v39, v192, v193
	v_cvt_pk_bf16_f32 v40, v194, v195
	v_cvt_pk_bf16_f32 v41, v148, v149
	v_lshrrev_b32_e32 v35, 1, v217
	global_store_dwordx4 v35, v[38:41], s[30:31] offset:256
	ds_bpermute_b32 v36, v140, v34
	s_waitcnt lgkmcnt(0)
	v_add_f32_e32 v34, v34, v36
	ds_bpermute_b32 v36, v141, v34
	s_and_saveexec_b64 s[48:49], s[38:39]
	s_cbranch_execz .Lple_nostat_5
	s_waitcnt lgkmcnt(0)
	v_add_f32_e32 v34, v34, v36
	global_store_dword v177, v34, s[76:77] offset:576

.Lple_skip_11:
	v_add_u32_e32 v217, 0xb0000, v176
	v_lshrrev_b32_e32 v37, 1, v217
	global_load_dwordx4 v[242:245], v37, s[36:37]
	global_load_dwordx4 v[246:249], v217, s[16:17]
	global_load_dwordx4 v[186:189], v217, s[16:17] offset:16
	v_mul_f32_e32 v26, v26, v174
	v_mul_f32_e32 v27, v27, v174
	v_mul_f32_e32 v28, v28, v174
	v_mul_f32_e32 v29, v29, v174
	v_mul_f32_e32 v30, v30, v174
	v_mul_f32_e32 v31, v31, v174
	v_mul_f32_e32 v32, v32, v174
	v_mul_f32_e32 v33, v33, v174
	v_mul_f32_e32 v26, 0xbfb8aa3b, v26
	v_mul_f32_e32 v27, 0xbfb8aa3b, v27
	v_mul_f32_e32 v28, 0xbfb8aa3b, v28
	v_mul_f32_e32 v29, 0xbfb8aa3b, v29
	v_mul_f32_e32 v30, 0xbfb8aa3b, v30
	v_mul_f32_e32 v31, 0xbfb8aa3b, v31
	v_mul_f32_e32 v32, 0xbfb8aa3b, v32
	v_mul_f32_e32 v33, 0xbfb8aa3b, v33
	v_exp_f32_e32 v26, v26
	v_exp_f32_e32 v27, v27
	v_exp_f32_e32 v28, v28
	v_exp_f32_e32 v29, v29
	v_exp_f32_e32 v30, v30
	v_exp_f32_e32 v31, v31
	v_exp_f32_e32 v32, v32
	v_exp_f32_e32 v33, v33
	v_add_f32_e32 v26, 1.0, v26
	v_add_f32_e32 v27, 1.0, v27
	v_add_f32_e32 v28, 1.0, v28
	v_add_f32_e32 v29, 1.0, v29
	v_add_f32_e32 v30, 1.0, v30
	v_add_f32_e32 v31, 1.0, v31
	v_add_f32_e32 v32, 1.0, v32
	v_add_f32_e32 v33, 1.0, v33
	v_rcp_f32_e32 v26, v26
	v_rcp_f32_e32 v27, v27
	v_rcp_f32_e32 v28, v28
	v_rcp_f32_e32 v29, v29
	v_rcp_f32_e32 v30, v30
	v_rcp_f32_e32 v31, v31
	v_rcp_f32_e32 v32, v32
	v_rcp_f32_e32 v33, v33
	s_waitcnt vmcnt(10)
	v_lshlrev_b32_e32 v190, 16, v218
	v_and_b32_e32 v191, 0xffff0000, v218
	v_lshlrev_b32_e32 v192, 16, v219
	v_and_b32_e32 v193, 0xffff0000, v219
	v_lshlrev_b32_e32 v194, 16, v220
	v_and_b32_e32 v195, 0xffff0000, v220
	v_lshlrev_b32_e32 v148, 16, v221
	v_and_b32_e32 v149, 0xffff0000, v221
	v_pk_fma_f32 v[222:223], v[30:31], v[190:191], v[222:223]
	v_pk_fma_f32 v[224:225], v[32:33], v[192:193], v[224:225]
	v_pk_fma_f32 v[226:227], v[26:27], v[194:195], v[226:227]
	v_pk_fma_f32 v[228:229], v[28:29], v[148:149], v[228:229]
	global_store_dwordx4 v172, v[222:225], s[16:17]
	global_store_dwordx4 v172, v[226:229], s[16:17] offset:16
	s_and_b64 vcc, exec, s[2:3]
	s_cbranch_vccnz .Lple_skip_12
	v_mul_f32_e32 v26, v223, v223
	v_mul_f32_e32 v27, v225, v225
	v_fmac_f32_e32 v26, v222, v222
	v_fmac_f32_e32 v27, v224, v224
	v_add_f32_e32 v26, v26, v27
	v_mul_f32_e32 v27, v227, v227
	v_fmac_f32_e32 v27, v226, v226
	v_add_f32_e32 v26, v27, v26
	v_mul_f32_e32 v27, v229, v229
	v_fmac_f32_e32 v27, v228, v228
	v_add_f32_e32 v26, v27, v26
	v_pk_mul_f32 v[190:191], v[62:63], v[222:223]
	v_pk_mul_f32 v[192:193], v[64:65], v[224:225]
	v_pk_mul_f32 v[194:195], v[58:59], v[226:227]
	v_pk_mul_f32 v[148:149], v[60:61], v[228:229]
	v_cvt_pk_bf16_f32 v30, v190, v191
	v_cvt_pk_bf16_f32 v31, v192, v193
	v_cvt_pk_bf16_f32 v32, v194, v195
	v_cvt_pk_bf16_f32 v33, v148, v149
	v_lshrrev_b32_e32 v28, 1, v172
	global_store_dwordx4 v28, v[30:33], s[30:31]
.Lple_skip_12:
	v_add_u32_e32 v172, 0xb0000, v176
	v_lshrrev_b32_e32 v29, 1, v172
	global_load_dwordx4 v[218:221], v29, s[36:37] offset:256
	global_load_dwordx4 v[222:225], v172, s[16:17] offset:512
	global_load_dwordx4 v[226:229], v172, s[16:17] offset:528
	v_mul_f32_e32 v18, v18, v174
	v_mul_f32_e32 v19, v19, v174
	v_mul_f32_e32 v20, v20, v174
	v_mul_f32_e32 v21, v21, v174
	v_mul_f32_e32 v22, v22, v174
	v_mul_f32_e32 v23, v23, v174
	v_mul_f32_e32 v24, v24, v174
	v_mul_f32_e32 v25, v25, v174
	v_mul_f32_e32 v18, 0xbfb8aa3b, v18
	v_mul_f32_e32 v19, 0xbfb8aa3b, v19
	v_mul_f32_e32 v20, 0xbfb8aa3b, v20
	v_mul_f32_e32 v21, 0xbfb8aa3b, v21
	v_mul_f32_e32 v22, 0xbfb8aa3b, v22
	v_mul_f32_e32 v23, 0xbfb8aa3b, v23
	v_mul_f32_e32 v24, 0xbfb8aa3b, v24
	v_mul_f32_e32 v25, 0xbfb8aa3b, v25
	v_exp_f32_e32 v18, v18
	v_exp_f32_e32 v19, v19
	v_exp_f32_e32 v20, v20
	v_exp_f32_e32 v21, v21
	v_exp_f32_e32 v22, v22
	v_exp_f32_e32 v23, v23
	v_exp_f32_e32 v24, v24
	v_exp_f32_e32 v25, v25
	v_add_f32_e32 v18, 1.0, v18
	v_add_f32_e32 v19, 1.0, v19
	v_add_f32_e32 v20, 1.0, v20
	v_add_f32_e32 v21, 1.0, v21
	v_add_f32_e32 v22, 1.0, v22
	v_add_f32_e32 v23, 1.0, v23
	v_add_f32_e32 v24, 1.0, v24
	v_add_f32_e32 v25, 1.0, v25
	v_rcp_f32_e32 v18, v18
	v_rcp_f32_e32 v19, v19
	v_rcp_f32_e32 v20, v20
	v_rcp_f32_e32 v21, v21
	v_rcp_f32_e32 v22, v22
	v_rcp_f32_e32 v23, v23
	v_rcp_f32_e32 v24, v24
	v_rcp_f32_e32 v25, v25
	s_waitcnt vmcnt(10)
	v_lshlrev_b32_e32 v190, 16, v230
	v_and_b32_e32 v191, 0xffff0000, v230
	v_lshlrev_b32_e32 v192, 16, v231
	v_and_b32_e32 v193, 0xffff0000, v231
	v_lshlrev_b32_e32 v194, 16, v232
	v_and_b32_e32 v195, 0xffff0000, v232
	v_lshlrev_b32_e32 v148, 16, v233
	v_and_b32_e32 v149, 0xffff0000, v233
	v_pk_fma_f32 v[234:235], v[22:23], v[190:191], v[234:235]
	v_pk_fma_f32 v[236:237], v[24:25], v[192:193], v[236:237]
	v_pk_fma_f32 v[238:239], v[18:19], v[194:195], v[238:239]
	v_pk_fma_f32 v[240:241], v[20:21], v[148:149], v[240:241]
	global_store_dwordx4 v173, v[234:237], s[16:17] offset:512
	global_store_dwordx4 v173, v[238:241], s[16:17] offset:528
	s_and_b64 vcc, exec, s[2:3]
	s_cbranch_vccnz .Lple_skip_13
	v_mul_f32_e32 v18, v234, v234
	v_mul_f32_e32 v19, v235, v235
	v_mul_f32_e32 v20, v236, v236
	v_mul_f32_e32 v21, v237, v237
	v_add_f32_e32 v18, v18, v19
	v_add_f32_e32 v20, v20, v21
	v_mul_f32_e32 v19, v238, v238
	v_mul_f32_e32 v21, v239, v239
	v_add_f32_e32 v18, v18, v20
	v_add_f32_e32 v19, v19, v21
	v_mul_f32_e32 v20, v240, v240
	v_mul_f32_e32 v21, v241, v241
	v_add_f32_e32 v18, v19, v18
	v_add_f32_e32 v20, v20, v21
	v_add_f32_e32 v18, v20, v18
	v_add_f32_e32 v18, v26, v18
	v_pk_mul_f32 v[190:191], v[54:55], v[234:235]
	v_pk_mul_f32 v[192:193], v[56:57], v[236:237]
	v_pk_mul_f32 v[194:195], v[50:51], v[238:239]
	v_pk_mul_f32 v[148:149], v[52:53], v[240:241]
	v_cvt_pk_bf16_f32 v22, v190, v191
	v_cvt_pk_bf16_f32 v23, v192, v193
	v_cvt_pk_bf16_f32 v24, v194, v195
	v_cvt_pk_bf16_f32 v25, v148, v149
	v_lshrrev_b32_e32 v19, 1, v173
	global_store_dwordx4 v19, v[22:25], s[30:31] offset:256
	ds_bpermute_b32 v20, v140, v18
	s_waitcnt lgkmcnt(0)
	v_add_f32_e32 v18, v18, v20
	ds_bpermute_b32 v20, v141, v18
	s_and_saveexec_b64 s[48:49], s[38:39]
	s_cbranch_execz .Lple_nostat_6
	s_waitcnt lgkmcnt(0)
	v_add_f32_e32 v18, v18, v20
	global_store_dword v177, v18, s[76:77] offset:640

.Lple_skip_13:
	v_mul_f32_e32 v10, v10, v175
	v_mul_f32_e32 v11, v11, v175
	v_mul_f32_e32 v12, v12, v175
	v_mul_f32_e32 v13, v13, v175
	v_mul_f32_e32 v14, v14, v175
	v_mul_f32_e32 v15, v15, v175
	v_mul_f32_e32 v16, v16, v175
	v_mul_f32_e32 v17, v17, v175
	v_mul_f32_e32 v10, 0xbfb8aa3b, v10
	v_mul_f32_e32 v11, 0xbfb8aa3b, v11
	v_mul_f32_e32 v12, 0xbfb8aa3b, v12
	v_mul_f32_e32 v13, 0xbfb8aa3b, v13
	v_mul_f32_e32 v14, 0xbfb8aa3b, v14
	v_mul_f32_e32 v15, 0xbfb8aa3b, v15
	v_mul_f32_e32 v16, 0xbfb8aa3b, v16
	v_mul_f32_e32 v17, 0xbfb8aa3b, v17
	v_exp_f32_e32 v10, v10
	v_exp_f32_e32 v11, v11
	v_exp_f32_e32 v12, v12
	v_exp_f32_e32 v13, v13
	v_exp_f32_e32 v14, v14
	v_exp_f32_e32 v15, v15
	v_exp_f32_e32 v16, v16
	v_exp_f32_e32 v17, v17
	v_add_f32_e32 v10, 1.0, v10
	v_add_f32_e32 v11, 1.0, v11
	v_add_f32_e32 v12, 1.0, v12
	v_add_f32_e32 v13, 1.0, v13
	v_add_f32_e32 v14, 1.0, v14
	v_add_f32_e32 v15, 1.0, v15
	v_add_f32_e32 v16, 1.0, v16
	v_add_f32_e32 v17, 1.0, v17
	v_rcp_f32_e32 v10, v10
	v_rcp_f32_e32 v11, v11
	v_rcp_f32_e32 v12, v12
	v_rcp_f32_e32 v13, v13
	v_rcp_f32_e32 v14, v14
	v_rcp_f32_e32 v15, v15
	v_rcp_f32_e32 v16, v16
	v_rcp_f32_e32 v17, v17
	s_waitcnt vmcnt(7)
	v_lshlrev_b32_e32 v190, 16, v242
	v_and_b32_e32 v191, 0xffff0000, v242
	v_lshlrev_b32_e32 v192, 16, v243
	v_and_b32_e32 v193, 0xffff0000, v243
	v_lshlrev_b32_e32 v194, 16, v244
	v_and_b32_e32 v195, 0xffff0000, v244
	v_lshlrev_b32_e32 v148, 16, v245
	v_and_b32_e32 v149, 0xffff0000, v245
	v_pk_fma_f32 v[246:247], v[14:15], v[190:191], v[246:247]
	v_pk_fma_f32 v[248:249], v[16:17], v[192:193], v[248:249]
	v_pk_fma_f32 v[186:187], v[10:11], v[194:195], v[186:187]
	v_pk_fma_f32 v[188:189], v[12:13], v[148:149], v[188:189]
	global_store_dwordx4 v217, v[246:249], s[16:17]
	global_store_dwordx4 v217, v[186:189], s[16:17] offset:16
	s_and_b64 vcc, exec, s[2:3]
	s_cbranch_vccnz .Lple_skip_14
	v_mul_f32_e32 v10, v247, v247
	v_mul_f32_e32 v11, v249, v249
	v_fmac_f32_e32 v10, v246, v246
	v_fmac_f32_e32 v11, v248, v248
	v_add_f32_e32 v10, v10, v11
	v_mul_f32_e32 v11, v187, v187
	v_fmac_f32_e32 v11, v186, v186
	v_add_f32_e32 v10, v11, v10
	v_mul_f32_e32 v11, v189, v189
	v_fmac_f32_e32 v11, v188, v188
	v_add_f32_e32 v10, v11, v10
	v_pk_mul_f32 v[190:191], v[62:63], v[246:247]
	v_pk_mul_f32 v[192:193], v[64:65], v[248:249]
	v_pk_mul_f32 v[194:195], v[58:59], v[186:187]
	v_pk_mul_f32 v[148:149], v[60:61], v[188:189]
	v_cvt_pk_bf16_f32 v14, v190, v191
	v_cvt_pk_bf16_f32 v15, v192, v193
	v_cvt_pk_bf16_f32 v16, v194, v195
	v_cvt_pk_bf16_f32 v17, v148, v149
	v_lshrrev_b32_e32 v12, 1, v217
	global_store_dwordx4 v12, v[14:17], s[30:31]
.Lple_skip_14:
	v_mul_f32_e32 v2, v2, v175
	v_mul_f32_e32 v3, v3, v175
	v_mul_f32_e32 v4, v4, v175
	v_mul_f32_e32 v5, v5, v175
	v_mul_f32_e32 v6, v6, v175
	v_mul_f32_e32 v7, v7, v175
	v_mul_f32_e32 v8, v8, v175
	v_mul_f32_e32 v9, v9, v175
	v_mul_f32_e32 v2, 0xbfb8aa3b, v2
	v_mul_f32_e32 v3, 0xbfb8aa3b, v3
	v_mul_f32_e32 v4, 0xbfb8aa3b, v4
	v_mul_f32_e32 v5, 0xbfb8aa3b, v5
	v_mul_f32_e32 v6, 0xbfb8aa3b, v6
	v_mul_f32_e32 v7, 0xbfb8aa3b, v7
	v_mul_f32_e32 v8, 0xbfb8aa3b, v8
	v_mul_f32_e32 v9, 0xbfb8aa3b, v9
	v_exp_f32_e32 v2, v2
	v_exp_f32_e32 v3, v3
	v_exp_f32_e32 v4, v4
	v_exp_f32_e32 v5, v5
	v_exp_f32_e32 v6, v6
	v_exp_f32_e32 v7, v7
	v_exp_f32_e32 v8, v8
	v_exp_f32_e32 v9, v9
	v_add_f32_e32 v2, 1.0, v2
	v_add_f32_e32 v3, 1.0, v3
	v_add_f32_e32 v4, 1.0, v4
	v_add_f32_e32 v5, 1.0, v5
	v_add_f32_e32 v6, 1.0, v6
	v_add_f32_e32 v7, 1.0, v7
	v_add_f32_e32 v8, 1.0, v8
	v_add_f32_e32 v9, 1.0, v9
	v_rcp_f32_e32 v2, v2
	v_rcp_f32_e32 v3, v3
	v_rcp_f32_e32 v4, v4
	v_rcp_f32_e32 v5, v5
	v_rcp_f32_e32 v6, v6
	v_rcp_f32_e32 v7, v7
	v_rcp_f32_e32 v8, v8
	v_rcp_f32_e32 v9, v9
	s_waitcnt vmcnt(4)
	v_lshlrev_b32_e32 v190, 16, v218
	v_and_b32_e32 v191, 0xffff0000, v218
	v_lshlrev_b32_e32 v192, 16, v219
	v_and_b32_e32 v193, 0xffff0000, v219
	v_lshlrev_b32_e32 v194, 16, v220
	v_and_b32_e32 v195, 0xffff0000, v220
	v_lshlrev_b32_e32 v148, 16, v221
	v_and_b32_e32 v149, 0xffff0000, v221
	v_pk_fma_f32 v[222:223], v[6:7], v[190:191], v[222:223]
	v_pk_fma_f32 v[224:225], v[8:9], v[192:193], v[224:225]
	v_pk_fma_f32 v[226:227], v[2:3], v[194:195], v[226:227]
	v_pk_fma_f32 v[228:229], v[4:5], v[148:149], v[228:229]
	global_store_dwordx4 v172, v[222:225], s[16:17] offset:512
	global_store_dwordx4 v172, v[226:229], s[16:17] offset:528
	s_and_b64 vcc, exec, s[2:3]
	s_cbranch_vccnz .Lple_skip_15
	v_mul_f32_e32 v2, v222, v222
	v_mul_f32_e32 v3, v223, v223
	v_mul_f32_e32 v4, v224, v224
	v_mul_f32_e32 v5, v225, v225
	v_add_f32_e32 v2, v2, v3
	v_add_f32_e32 v4, v4, v5
	v_mul_f32_e32 v3, v226, v226
	v_mul_f32_e32 v5, v227, v227
	v_add_f32_e32 v2, v2, v4
	v_add_f32_e32 v3, v3, v5
	v_mul_f32_e32 v4, v228, v228
	v_mul_f32_e32 v5, v229, v229
	v_add_f32_e32 v2, v3, v2
	v_add_f32_e32 v4, v4, v5
	v_add_f32_e32 v2, v4, v2
	v_add_f32_e32 v2, v10, v2
	v_pk_mul_f32 v[190:191], v[54:55], v[222:223]
	v_pk_mul_f32 v[192:193], v[56:57], v[224:225]
	v_pk_mul_f32 v[194:195], v[50:51], v[226:227]
	v_pk_mul_f32 v[148:149], v[52:53], v[228:229]
	v_cvt_pk_bf16_f32 v6, v190, v191
	v_cvt_pk_bf16_f32 v7, v192, v193
	v_cvt_pk_bf16_f32 v8, v194, v195
	v_cvt_pk_bf16_f32 v9, v148, v149
	v_lshrrev_b32_e32 v3, 1, v172
	global_store_dwordx4 v3, v[6:9], s[30:31] offset:256
	ds_bpermute_b32 v4, v140, v2
	s_waitcnt lgkmcnt(0)
	v_add_f32_e32 v2, v2, v4
	ds_bpermute_b32 v4, v141, v2
	s_and_saveexec_b64 s[48:49], s[38:39]
	s_cbranch_execz .Lple_nostat_7
	s_waitcnt lgkmcnt(0)
	v_add_f32_e32 v2, v2, v4
	global_store_dword v177, v2, s[76:77] offset:704

.Lple_skip_15:
	s_mov_b64 s[48:49], 0x2c000
.LBB0_1023:
	s_andn2_b64 vcc, exec, s[40:41]
	s_mov_b64 s[2:3], -1
	s_cbranch_vccnz .LBB0_955
	s_andn2_b64 vcc, exec, s[0:1]
	s_cbranch_vccnz .LBB0_954
	s_barrier
	s_branch .LBB0_954
